# loop-exit edge: MLP-up rstd LDS reads issued at K-loop exit, before the epilogue-align barrier
# speedup vs baseline: 1.0062x; 1.0062x over previous
; #define PG8_LAS __attribute__((address_space(3)))
; #define PG8_BAR __builtin_amdgcn_s_barrier()
; __device__ __forceinline__ void rstd_from_lds(PG8_LAS unsigned char* lds, int wr, int fr, float (&rs)[2][4]) {
; #pragma unroll
;     for (int ai = 0; ai < 2; ++ai)
; #pragma unroll
;         for (int m = 0; m < 4; ++m) rs[ai][m] = ((const PG8_LAS float*)(lds + RSTD_OFF))[ai * HALF + wr * 64 + m * 16 + fr];
;     ...
;         if (wr == 0) PG8_BAR;
;         if (!has_next && wmat && gtid * 128u < wbytes) asm volatile("global_load_dword %0, %1, off" : "+v"(warmm) : "v"(wmat + (size_t)gtid * 128u) : "memory");
.Lpeel_exit_504:
	ds_read2_b32 v[158:159], v153 offset1:16
	ds_read2_b32 v[160:161], v153 offset0:32 offset1:48
	ds_read2_b32 v[146:147], v153 offset0:128 offset1:144
	ds_read2_b32 v[144:145], v153 offset0:160 offset1:176
	s_and_b64 vcc, exec, s[6:7]
	s_cbranch_vccz .LBB0_515
	s_barrier
	s_nor_b64 s[14:15], s[36:37], s[38:39]
	s_and_saveexec_b64 s[12:13], s[14:15]
	s_cbranch_execnz .LBB0_516

; __device__ __forceinline__ unsigned cvt_pk_bf16(float lo, float hi) { unsigned r; asm volatile("v_cvt_pk_bf16_f32 %0, %1, %2" : "=v"(r) : "v"(lo), "v"(hi)); return r; }
;     __device__ __forceinline__ void operator()(AccT& acc, const Unit& u, int wr, int wc, int fr, int fq, PG8_LAS unsigned char* lds) const {
;         const int rowbase = u.pm * BM + wr * 64 + fr, col0 = u.pn * BM + wc * 32 + 8 * fq;
;         float rs[2][4]; rstd_from_lds(lds, wr, fr, rs);
; #pragma unroll
;         for (int ai = 0; ai < 2; ++ai)
; #pragma unroll
;             for (int m = 0; m < 4; ++m) { bf16_t* rowp = out + (size_t)(rowbase + ai * HALF + m * 16) * 4096 + col0; const float r = rs[ai][m];
; #pragma unroll
;                 for (int bj = 0; bj < 2; ++bj) { f32x4 v0 = acc[ai][bj][m][0] * r, v1 = acc[ai][bj][m][1] * r;
; #pragma unroll
;                     for (int j = 0; j < 4; ++j) { v0[j] = fmaxf(v0[j], 0.f); v0[j] *= v0[j]; v1[j] = fmaxf(v1[j], 0.f); v1[j] *= v1[j]; }
;                     u32x4 w; w.x = cvt_pk_bf16(v0[0], v0[1]); w.y = cvt_pk_bf16(v0[2], v0[3]); w.z = cvt_pk_bf16(v1[0], v1[1]); w.w = cvt_pk_bf16(v1[2], v1[3]);
;                     *(u32x4*)(rowp + bj * HALF) = w; } }
.LBB0_509:
	v_lshl_add_u32 v156, s10, 8, v148
	s_waitcnt lgkmcnt(0)
	v_pk_mul_f32 v[120:121], v[120:121], v[158:159] op_sel_hi:[1,0]
	v_lshl_or_b32 v142, s46, 8, v151
	v_ashrrev_i32_e32 v157, 31, v156
	v_pk_mul_f32 v[124:125], v[124:125], v[158:159] op_sel_hi:[1,0]
	v_pk_mul_f32 v[122:123], v[122:123], v[158:159] op_sel_hi:[1,0]
	v_max_f32_e32 v120, 0, v120
	v_ashrrev_i32_e32 v143, 31, v142
	v_lshlrev_b64 v[162:163], 13, v[156:157]
	v_pk_mul_f32 v[126:127], v[126:127], v[158:159] op_sel_hi:[1,0]
	v_mul_f32_e32 v155, v120, v120
	v_max_f32_e32 v120, 0, v125
	v_max_f32_e32 v121, 0, v121
	v_max_f32_e32 v122, 0, v122
	v_lshl_add_u64 v[162:163], s[2:3], 0, v[162:163]
	v_lshlrev_b64 v[164:165], 1, v[142:143]
	v_max_f32_e32 v124, 0, v124
	v_mul_f32_e32 v120, v120, v120
	v_mul_f32_e32 v125, v121, v121
	v_max_f32_e32 v121, 0, v126
	v_mul_f32_e32 v126, v122, v122
	v_max_f32_e32 v122, 0, v127
	v_max_f32_e32 v123, 0, v123
	v_pk_mul_f32 v[114:115], v[114:115], v[158:159] op_sel_hi:[1,0]
	v_pk_mul_f32 v[112:113], v[112:113], v[158:159] op_sel_hi:[1,0]
	v_lshl_add_u64 v[142:143], v[162:163], 0, v[164:165]
	v_mul_f32_e32 v124, v124, v124
	v_mul_f32_e32 v121, v121, v121
	v_mul_f32_e32 v122, v122, v122
	v_mul_f32_e32 v123, v123, v123
	v_cvt_pk_bf16_f32 v120, v124, v120
	v_pk_mul_f32 v[118:119], v[118:119], v[158:159] op_sel_hi:[1,0]
	v_pk_mul_f32 v[116:117], v[116:117], v[158:159] op_sel_hi:[1,0]
	v_max_f32_e32 v112, 0, v112
	v_max_f32_e32 v113, 0, v113
	v_max_f32_e32 v114, 0, v114
	v_cvt_pk_bf16_f32 v121, v121, v122
	v_cvt_pk_bf16_f32 v122, v155, v125
	v_cvt_pk_bf16_f32 v123, v126, v123
	global_store_dwordx4 v[142:143], v[120:123], off
	v_max_f32_e32 v116, 0, v116
	v_max_f32_e32 v115, 0, v115
	v_mul_f32_e32 v120, v112, v112
	v_max_f32_e32 v112, 0, v117
	v_mul_f32_e32 v117, v113, v113
	v_max_f32_e32 v113, 0, v118
	v_mul_f32_e32 v118, v114, v114
	v_max_f32_e32 v114, 0, v119
	v_mul_f32_e32 v112, v112, v112
	v_mul_f32_e32 v113, v113, v113
	v_mul_f32_e32 v114, v114, v114
	v_mul_f32_e32 v116, v116, v116
	v_mul_f32_e32 v115, v115, v115
	v_cvt_pk_bf16_f32 v112, v116, v112
	v_cvt_pk_bf16_f32 v113, v113, v114
	v_cvt_pk_bf16_f32 v114, v120, v117
	v_cvt_pk_bf16_f32 v115, v118, v115
	global_store_dwordx4 v[142:143], v[112:115], off offset:256
	v_pk_mul_f32 v[88:89], v[88:89], v[160:161] op_sel_hi:[1,0]
	v_pk_mul_f32 v[92:93], v[92:93], v[160:161] op_sel_hi:[1,0]
	v_mov_b32_e32 v114, v159
	v_or_b32_e32 v112, 16, v156
	v_pk_mul_f32 v[104:105], v[104:105], v[114:115] op_sel_hi:[1,0]
	v_ashrrev_i32_e32 v113, 31, v112
	v_pk_mul_f32 v[108:109], v[108:109], v[114:115] op_sel_hi:[1,0]
	v_pk_mul_f32 v[106:107], v[106:107], v[114:115] op_sel_hi:[1,0]
	v_max_f32_e32 v104, 0, v104
	v_lshlrev_b64 v[112:113], 13, v[112:113]
	v_pk_mul_f32 v[110:111], v[110:111], v[114:115] op_sel_hi:[1,0]
	v_mul_f32_e32 v115, v104, v104
	v_max_f32_e32 v104, 0, v109
	v_max_f32_e32 v105, 0, v105
	v_max_f32_e32 v106, 0, v106
	v_lshl_add_u64 v[112:113], s[2:3], 0, v[112:113]
	v_max_f32_e32 v108, 0, v108
	v_mul_f32_e32 v104, v104, v104
	v_mul_f32_e32 v109, v105, v105
	v_max_f32_e32 v105, 0, v110
	v_mul_f32_e32 v110, v106, v106
	v_max_f32_e32 v106, 0, v111
	v_max_f32_e32 v107, 0, v107
	v_pk_mul_f32 v[96:97], v[96:97], v[114:115] op_sel_hi:[1,0]
	v_lshl_add_u64 v[112:113], v[112:113], 0, v[164:165]
	v_mul_f32_e32 v108, v108, v108
	v_mul_f32_e32 v105, v105, v105
	v_mul_f32_e32 v106, v106, v106
	v_mul_f32_e32 v107, v107, v107
	v_cvt_pk_bf16_f32 v104, v108, v104
	v_pk_mul_f32 v[100:101], v[100:101], v[114:115] op_sel_hi:[1,0]
	v_pk_mul_f32 v[98:99], v[98:99], v[114:115] op_sel_hi:[1,0]
	v_max_f32_e32 v96, 0, v96
	v_cvt_pk_bf16_f32 v105, v105, v106
	v_cvt_pk_bf16_f32 v106, v115, v109
	v_cvt_pk_bf16_f32 v107, v110, v107
	global_store_dwordx4 v[112:113], v[104:107], off
	v_pk_mul_f32 v[102:103], v[102:103], v[114:115] op_sel_hi:[1,0]
	v_max_f32_e32 v97, 0, v97
	v_mul_f32_e32 v104, v96, v96
	v_max_f32_e32 v96, 0, v101
	v_max_f32_e32 v98, 0, v98
	v_max_f32_e32 v100, 0, v100
	v_mul_f32_e32 v96, v96, v96
	v_mul_f32_e32 v101, v97, v97
	v_max_f32_e32 v97, 0, v102
	v_mul_f32_e32 v102, v98, v98
	v_max_f32_e32 v98, 0, v103
	v_max_f32_e32 v99, 0, v99
	v_mul_f32_e32 v100, v100, v100
	v_mul_f32_e32 v97, v97, v97
	v_mul_f32_e32 v98, v98, v98
	v_mul_f32_e32 v99, v99, v99
	v_cvt_pk_bf16_f32 v96, v100, v96
	v_cvt_pk_bf16_f32 v97, v97, v98
	v_cvt_pk_bf16_f32 v98, v104, v101
	v_cvt_pk_bf16_f32 v99, v102, v99
	global_store_dwordx4 v[112:113], v[96:99], off offset:256
	v_pk_mul_f32 v[90:91], v[90:91], v[160:161] op_sel_hi:[1,0]
	v_max_f32_e32 v88, 0, v88
	v_or_b32_e32 v96, 32, v156
	v_ashrrev_i32_e32 v97, 31, v96
	v_lshlrev_b64 v[96:97], 13, v[96:97]
	v_pk_mul_f32 v[94:95], v[94:95], v[160:161] op_sel_hi:[1,0]
	v_mul_f32_e32 v98, v88, v88
	v_max_f32_e32 v88, 0, v93
	v_max_f32_e32 v89, 0, v89
	v_max_f32_e32 v90, 0, v90
	v_lshl_add_u64 v[96:97], s[2:3], 0, v[96:97]
	v_max_f32_e32 v92, 0, v92
	v_mul_f32_e32 v88, v88, v88
	v_mul_f32_e32 v93, v89, v89
	v_max_f32_e32 v89, 0, v94
	v_mul_f32_e32 v94, v90, v90
	v_max_f32_e32 v90, 0, v95
	v_max_f32_e32 v91, 0, v91
	v_pk_mul_f32 v[82:83], v[82:83], v[160:161] op_sel_hi:[1,0]
	v_pk_mul_f32 v[80:81], v[80:81], v[160:161] op_sel_hi:[1,0]
	v_lshl_add_u64 v[96:97], v[96:97], 0, v[164:165]
	v_mul_f32_e32 v92, v92, v92
	v_mul_f32_e32 v89, v89, v89
	v_mul_f32_e32 v90, v90, v90
	v_mul_f32_e32 v91, v91, v91
	v_cvt_pk_bf16_f32 v88, v92, v88
	v_pk_mul_f32 v[86:87], v[86:87], v[160:161] op_sel_hi:[1,0]
	v_pk_mul_f32 v[84:85], v[84:85], v[160:161] op_sel_hi:[1,0]
	v_max_f32_e32 v80, 0, v80
	v_max_f32_e32 v81, 0, v81
	v_max_f32_e32 v82, 0, v82
	v_cvt_pk_bf16_f32 v89, v89, v90
	v_cvt_pk_bf16_f32 v90, v98, v93
; __device__ __forceinline__ unsigned cvt_pk_bf16(float lo, float hi) { unsigned r; asm volatile("v_cvt_pk_bf16_f32 %0, %1, %2" : "=v"(r) : "v"(lo), "v"(hi)); return r; }
;     __device__ __forceinline__ void operator()(AccT& acc, const Unit& u, int wr, int wc, int fr, int fq, PG8_LAS unsigned char* lds) const {
;     ...
;             for (int m = 0; m < 4; ++m) { bf16_t* rowp = out + (size_t)(rowbase + ai * HALF + m * 16) * 4096 + col0; const float r = rs[ai][m];
; #pragma unroll
;                 for (int bj = 0; bj < 2; ++bj) { f32x4 v0 = acc[ai][bj][m][0] * r, v1 = acc[ai][bj][m][1] * r;
; #pragma unroll
;                     for (int j = 0; j < 4; ++j) { v0[j] = fmaxf(v0[j], 0.f); v0[j] *= v0[j]; v1[j] = fmaxf(v1[j], 0.f); v1[j] *= v1[j]; }
;                     u32x4 w; w.x = cvt_pk_bf16(v0[0], v0[1]); w.y = cvt_pk_bf16(v0[2], v0[3]); w.z = cvt_pk_bf16(v1[0], v1[1]); w.w = cvt_pk_bf16(v1[2], v1[3]);
;                     *(u32x4*)(rowp + bj * HALF) = w; } }
	v_cvt_pk_bf16_f32 v91, v94, v91
	global_store_dwordx4 v[96:97], v[88:91], off
	v_max_f32_e32 v84, 0, v84
	v_max_f32_e32 v83, 0, v83
	v_mul_f32_e32 v88, v80, v80
	v_max_f32_e32 v80, 0, v85
	v_mul_f32_e32 v85, v81, v81
	v_max_f32_e32 v81, 0, v86
	v_mul_f32_e32 v86, v82, v82
	v_max_f32_e32 v82, 0, v87
	v_mul_f32_e32 v80, v80, v80
	v_mul_f32_e32 v81, v81, v81
	v_mul_f32_e32 v82, v82, v82
	v_mul_f32_e32 v84, v84, v84
	v_mul_f32_e32 v83, v83, v83
	v_cvt_pk_bf16_f32 v80, v84, v80
	v_cvt_pk_bf16_f32 v81, v81, v82
	v_cvt_pk_bf16_f32 v82, v88, v85
	v_cvt_pk_bf16_f32 v83, v86, v83
	global_store_dwordx4 v[96:97], v[80:83], off offset:256
	v_pk_mul_f32 v[56:57], v[56:57], v[146:147] op_sel_hi:[1,0]
	v_pk_mul_f32 v[60:61], v[60:61], v[146:147] op_sel_hi:[1,0]
	v_mov_b32_e32 v82, v161
	v_or_b32_e32 v80, 48, v156
	v_pk_mul_f32 v[72:73], v[72:73], v[82:83] op_sel_hi:[1,0]
	v_ashrrev_i32_e32 v81, 31, v80
	v_pk_mul_f32 v[76:77], v[76:77], v[82:83] op_sel_hi:[1,0]
	v_pk_mul_f32 v[74:75], v[74:75], v[82:83] op_sel_hi:[1,0]
	v_max_f32_e32 v72, 0, v72
	v_lshlrev_b64 v[80:81], 13, v[80:81]
	v_pk_mul_f32 v[78:79], v[78:79], v[82:83] op_sel_hi:[1,0]
	v_mul_f32_e32 v83, v72, v72
	v_max_f32_e32 v72, 0, v77
	v_max_f32_e32 v73, 0, v73
	v_max_f32_e32 v74, 0, v74
	v_lshl_add_u64 v[80:81], s[2:3], 0, v[80:81]
	v_max_f32_e32 v76, 0, v76
	v_mul_f32_e32 v72, v72, v72
	v_mul_f32_e32 v77, v73, v73
	v_max_f32_e32 v73, 0, v78
	v_mul_f32_e32 v78, v74, v74
	v_max_f32_e32 v74, 0, v79
	v_max_f32_e32 v75, 0, v75
	v_pk_mul_f32 v[66:67], v[66:67], v[82:83] op_sel_hi:[1,0]
	v_pk_mul_f32 v[64:65], v[64:65], v[82:83] op_sel_hi:[1,0]
	v_lshl_add_u64 v[80:81], v[80:81], 0, v[164:165]
	v_mul_f32_e32 v76, v76, v76
	v_mul_f32_e32 v73, v73, v73
	v_mul_f32_e32 v74, v74, v74
	v_mul_f32_e32 v75, v75, v75
	v_cvt_pk_bf16_f32 v72, v76, v72
	v_pk_mul_f32 v[70:71], v[70:71], v[82:83] op_sel_hi:[1,0]
	v_pk_mul_f32 v[68:69], v[68:69], v[82:83] op_sel_hi:[1,0]
	v_max_f32_e32 v64, 0, v64
	v_max_f32_e32 v65, 0, v65
	v_max_f32_e32 v66, 0, v66
	v_cvt_pk_bf16_f32 v73, v73, v74
	v_cvt_pk_bf16_f32 v74, v83, v77
	v_cvt_pk_bf16_f32 v75, v78, v75
	global_store_dwordx4 v[80:81], v[72:75], off
	v_max_f32_e32 v68, 0, v68
	v_max_f32_e32 v67, 0, v67
	v_mul_f32_e32 v72, v64, v64
	v_max_f32_e32 v64, 0, v69
	v_mul_f32_e32 v69, v65, v65
	v_max_f32_e32 v65, 0, v70
	v_mul_f32_e32 v70, v66, v66
	v_max_f32_e32 v66, 0, v71
	v_mul_f32_e32 v64, v64, v64
	v_mul_f32_e32 v65, v65, v65
	v_mul_f32_e32 v66, v66, v66
	v_mul_f32_e32 v68, v68, v68
	v_mul_f32_e32 v67, v67, v67
	v_cvt_pk_bf16_f32 v64, v68, v64
	v_cvt_pk_bf16_f32 v65, v65, v66
	v_cvt_pk_bf16_f32 v66, v72, v69
	v_pk_mul_f32 v[58:59], v[58:59], v[146:147] op_sel_hi:[1,0]
	v_max_f32_e32 v56, 0, v56
	v_cvt_pk_bf16_f32 v67, v70, v67
	global_store_dwordx4 v[80:81], v[64:67], off offset:256
	s_mov_b64 s[10:11], 0x100000
	v_pk_mul_f32 v[62:63], v[62:63], v[146:147] op_sel_hi:[1,0]
	v_max_f32_e32 v60, 0, v60
	v_mul_f32_e32 v66, v56, v56
	v_max_f32_e32 v56, 0, v61
	v_max_f32_e32 v57, 0, v57
	v_max_f32_e32 v58, 0, v58
	v_lshl_add_u64 v[64:65], v[142:143], 0, s[10:11]
	v_mul_f32_e32 v60, v60, v60
	v_mul_f32_e32 v56, v56, v56
	v_mul_f32_e32 v61, v57, v57
	v_max_f32_e32 v57, 0, v62
	v_mul_f32_e32 v62, v58, v58
	v_max_f32_e32 v58, 0, v63
	s_mov_b32 s10, 0x100000
	v_mul_f32_e32 v57, v57, v57
	v_mul_f32_e32 v58, v58, v58
	v_max_f32_e32 v59, 0, v59
	v_cvt_pk_bf16_f32 v56, v60, v56
	v_add_co_u32_e32 v60, vcc, s10, v142
	v_pk_mul_f32 v[50:51], v[50:51], v[146:147] op_sel_hi:[1,0]
	v_pk_mul_f32 v[48:49], v[48:49], v[146:147] op_sel_hi:[1,0]
	v_mul_f32_e32 v59, v59, v59
	v_cvt_pk_bf16_f32 v57, v57, v58
	v_cvt_pk_bf16_f32 v58, v66, v61
	v_addc_co_u32_e32 v61, vcc, 0, v143, vcc
	v_pk_mul_f32 v[54:55], v[54:55], v[146:147] op_sel_hi:[1,0]
	v_pk_mul_f32 v[52:53], v[52:53], v[146:147] op_sel_hi:[1,0]
	v_max_f32_e32 v48, 0, v48
	v_max_f32_e32 v49, 0, v49
	v_max_f32_e32 v50, 0, v50
	v_cvt_pk_bf16_f32 v59, v62, v59
	global_store_dwordx4 v[60:61], v[56:59], off
	v_max_f32_e32 v52, 0, v52
	v_max_f32_e32 v51, 0, v51
	v_mul_f32_e32 v56, v48, v48
	v_max_f32_e32 v48, 0, v53
	v_mul_f32_e32 v53, v49, v49
	v_max_f32_e32 v49, 0, v54
	v_mul_f32_e32 v54, v50, v50
	v_max_f32_e32 v50, 0, v55
	v_mul_f32_e32 v48, v48, v48
	v_mul_f32_e32 v49, v49, v49
	v_mul_f32_e32 v50, v50, v50
	v_mul_f32_e32 v52, v52, v52
	v_mul_f32_e32 v51, v51, v51
	v_cvt_pk_bf16_f32 v48, v52, v48
	v_cvt_pk_bf16_f32 v49, v49, v50
	v_cvt_pk_bf16_f32 v50, v56, v53
	v_cvt_pk_bf16_f32 v51, v54, v51
	global_store_dwordx4 v[64:65], v[48:51], off offset:256
	s_mov_b64 s[10:11], 0x120000
	v_pk_mul_f32 v[24:25], v[24:25], v[144:145] op_sel_hi:[1,0]
	v_mov_b32_e32 v50, v147
	v_pk_mul_f32 v[40:41], v[40:41], v[50:51] op_sel_hi:[1,0]
	v_pk_mul_f32 v[44:45], v[44:45], v[50:51] op_sel_hi:[1,0]
	v_pk_mul_f32 v[42:43], v[42:43], v[50:51] op_sel_hi:[1,0]
	v_max_f32_e32 v40, 0, v40
	v_pk_mul_f32 v[46:47], v[46:47], v[50:51] op_sel_hi:[1,0]
	v_max_f32_e32 v44, 0, v44
	v_mul_f32_e32 v51, v40, v40
	v_max_f32_e32 v40, 0, v45
	v_max_f32_e32 v41, 0, v41
	v_max_f32_e32 v42, 0, v42
	v_lshl_add_u64 v[48:49], v[142:143], 0, s[10:11]
	v_mul_f32_e32 v44, v44, v44
	v_mul_f32_e32 v40, v40, v40
	v_mul_f32_e32 v45, v41, v41
	v_max_f32_e32 v41, 0, v46
; __device__ __forceinline__ unsigned cvt_pk_bf16(float lo, float hi) { unsigned r; asm volatile("v_cvt_pk_bf16_f32 %0, %1, %2" : "=v"(r) : "v"(lo), "v"(hi)); return r; }
; #define PG8_BAR __builtin_amdgcn_s_barrier()
;     __device__ __forceinline__ void operator()(AccT& acc, const Unit& u, int wr, int wc, int fr, int fq, PG8_LAS unsigned char* lds) const {
;     ...
;             for (int m = 0; m < 4; ++m) { bf16_t* rowp = out + (size_t)(rowbase + ai * HALF + m * 16) * 4096 + col0; const float r = rs[ai][m];
; #pragma unroll
;                 for (int bj = 0; bj < 2; ++bj) { f32x4 v0 = acc[ai][bj][m][0] * r, v1 = acc[ai][bj][m][1] * r;
; #pragma unroll
;                     for (int j = 0; j < 4; ++j) { v0[j] = fmaxf(v0[j], 0.f); v0[j] *= v0[j]; v1[j] = fmaxf(v1[j], 0.f); v1[j] *= v1[j]; }
;                     u32x4 w; w.x = cvt_pk_bf16(v0[0], v0[1]); w.y = cvt_pk_bf16(v0[2], v0[3]); w.z = cvt_pk_bf16(v1[0], v1[1]); w.w = cvt_pk_bf16(v1[2], v1[3]);
;                     *(u32x4*)(rowp + bj * HALF) = w; } }
;     ...
;         if (!has_next) break;
; #pragma unroll
;         for (int a = 0; a < 2; ++a)
; #pragma unroll
;             for (int b = 0; b < 2; ++b)
; #pragma unroll
;                 for (int m = 0; m < 4; ++m)
; #pragma unroll
;                     for (int n = 0; n < 2; ++n) acc[a][b][m][n] = (f32x4){0.f, 0.f, 0.f, 0.f};
;         cur = nxt; cB = nB; ++ui;
;         if (wr == 1) PG8_BAR;
	v_mul_f32_e32 v46, v42, v42
	v_max_f32_e32 v42, 0, v47
	s_mov_b32 s10, 0x120000
	v_mul_f32_e32 v41, v41, v41
	v_mul_f32_e32 v42, v42, v42
	v_max_f32_e32 v43, 0, v43
	v_cvt_pk_bf16_f32 v40, v44, v40
	v_add_co_u32_e32 v44, vcc, s10, v142
	v_pk_mul_f32 v[34:35], v[34:35], v[50:51] op_sel_hi:[1,0]
	v_pk_mul_f32 v[32:33], v[32:33], v[50:51] op_sel_hi:[1,0]
	v_mul_f32_e32 v43, v43, v43
	v_cvt_pk_bf16_f32 v41, v41, v42
	v_cvt_pk_bf16_f32 v42, v51, v45
	v_addc_co_u32_e32 v45, vcc, 0, v143, vcc
	v_pk_mul_f32 v[38:39], v[38:39], v[50:51] op_sel_hi:[1,0]
	v_pk_mul_f32 v[36:37], v[36:37], v[50:51] op_sel_hi:[1,0]
	v_max_f32_e32 v32, 0, v32
	v_max_f32_e32 v33, 0, v33
	v_max_f32_e32 v34, 0, v34
	v_cvt_pk_bf16_f32 v43, v46, v43
	global_store_dwordx4 v[44:45], v[40:43], off
	v_max_f32_e32 v36, 0, v36
	v_max_f32_e32 v35, 0, v35
	v_mul_f32_e32 v40, v32, v32
	v_max_f32_e32 v32, 0, v37
	v_mul_f32_e32 v37, v33, v33
	v_max_f32_e32 v33, 0, v38
	v_mul_f32_e32 v38, v34, v34
	v_max_f32_e32 v34, 0, v39
	v_mul_f32_e32 v32, v32, v32
	v_mul_f32_e32 v33, v33, v33
	v_mul_f32_e32 v34, v34, v34
	v_mul_f32_e32 v36, v36, v36
	v_mul_f32_e32 v35, v35, v35
	v_cvt_pk_bf16_f32 v32, v36, v32
	v_cvt_pk_bf16_f32 v33, v33, v34
	v_cvt_pk_bf16_f32 v34, v40, v37
	v_pk_mul_f32 v[28:29], v[28:29], v[144:145] op_sel_hi:[1,0]
	v_pk_mul_f32 v[26:27], v[26:27], v[144:145] op_sel_hi:[1,0]
	v_max_f32_e32 v24, 0, v24
	v_cvt_pk_bf16_f32 v35, v38, v35
	global_store_dwordx4 v[48:49], v[32:35], off offset:256
	s_mov_b64 s[10:11], 0x140000
	v_pk_mul_f32 v[30:31], v[30:31], v[144:145] op_sel_hi:[1,0]
	v_max_f32_e32 v28, 0, v28
	v_mul_f32_e32 v34, v24, v24
	v_max_f32_e32 v24, 0, v29
	v_max_f32_e32 v25, 0, v25
	v_max_f32_e32 v26, 0, v26
	v_lshl_add_u64 v[32:33], v[142:143], 0, s[10:11]
	v_mul_f32_e32 v28, v28, v28
	v_mul_f32_e32 v24, v24, v24
	v_mul_f32_e32 v29, v25, v25
	v_max_f32_e32 v25, 0, v30
	v_mul_f32_e32 v30, v26, v26
	v_max_f32_e32 v26, 0, v31
	s_mov_b32 s10, 0x140000
	v_mul_f32_e32 v25, v25, v25
	v_mul_f32_e32 v26, v26, v26
	v_max_f32_e32 v27, 0, v27
	v_cvt_pk_bf16_f32 v24, v28, v24
	v_add_co_u32_e32 v28, vcc, s10, v142
	v_pk_mul_f32 v[18:19], v[18:19], v[144:145] op_sel_hi:[1,0]
	v_pk_mul_f32 v[16:17], v[16:17], v[144:145] op_sel_hi:[1,0]
	v_mul_f32_e32 v27, v27, v27
	v_cvt_pk_bf16_f32 v25, v25, v26
	v_cvt_pk_bf16_f32 v26, v34, v29
	v_addc_co_u32_e32 v29, vcc, 0, v143, vcc
	v_pk_mul_f32 v[22:23], v[22:23], v[144:145] op_sel_hi:[1,0]
	v_pk_mul_f32 v[20:21], v[20:21], v[144:145] op_sel_hi:[1,0]
	v_max_f32_e32 v16, 0, v16
	v_max_f32_e32 v17, 0, v17
	v_max_f32_e32 v18, 0, v18
	v_cvt_pk_bf16_f32 v27, v30, v27
	global_store_dwordx4 v[28:29], v[24:27], off
	v_max_f32_e32 v20, 0, v20
	v_max_f32_e32 v19, 0, v19
	v_mul_f32_e32 v24, v16, v16
	v_max_f32_e32 v16, 0, v21
	v_mul_f32_e32 v21, v17, v17
	v_max_f32_e32 v17, 0, v22
	v_mul_f32_e32 v22, v18, v18
	v_max_f32_e32 v18, 0, v23
	v_mul_f32_e32 v16, v16, v16
	v_mul_f32_e32 v17, v17, v17
	v_mul_f32_e32 v18, v18, v18
	v_mul_f32_e32 v20, v20, v20
	v_mul_f32_e32 v19, v19, v19
	v_cvt_pk_bf16_f32 v16, v20, v16
	v_cvt_pk_bf16_f32 v17, v17, v18
	v_cvt_pk_bf16_f32 v18, v24, v21
	v_cvt_pk_bf16_f32 v19, v22, v19
	global_store_dwordx4 v[32:33], v[16:19], off offset:256
	s_mov_b64 s[10:11], 0x160000
	s_nop 0
	v_mov_b32_e32 v18, v145
	v_pk_mul_f32 v[8:9], v[8:9], v[18:19] op_sel_hi:[1,0]
	v_pk_mul_f32 v[12:13], v[12:13], v[18:19] op_sel_hi:[1,0]
	v_pk_mul_f32 v[10:11], v[10:11], v[18:19] op_sel_hi:[1,0]
	v_max_f32_e32 v8, 0, v8
	v_pk_mul_f32 v[14:15], v[14:15], v[18:19] op_sel_hi:[1,0]
	v_max_f32_e32 v12, 0, v12
	v_mul_f32_e32 v19, v8, v8
	v_max_f32_e32 v8, 0, v13
	v_max_f32_e32 v9, 0, v9
	v_max_f32_e32 v10, 0, v10
	v_lshl_add_u64 v[16:17], v[142:143], 0, s[10:11]
	v_mul_f32_e32 v12, v12, v12
	v_mul_f32_e32 v8, v8, v8
	v_mul_f32_e32 v13, v9, v9
	v_max_f32_e32 v9, 0, v14
	v_mul_f32_e32 v14, v10, v10
	v_max_f32_e32 v10, 0, v15
	s_mov_b32 s10, 0x160000
	v_mul_f32_e32 v9, v9, v9
	v_mul_f32_e32 v10, v10, v10
	v_max_f32_e32 v11, 0, v11
	v_cvt_pk_bf16_f32 v8, v12, v8
	v_add_co_u32_e32 v12, vcc, s10, v142
	v_pk_mul_f32 v[2:3], v[2:3], v[18:19] op_sel_hi:[1,0]
	v_pk_mul_f32 v[0:1], v[0:1], v[18:19] op_sel_hi:[1,0]
	v_mul_f32_e32 v11, v11, v11
	v_cvt_pk_bf16_f32 v9, v9, v10
	v_cvt_pk_bf16_f32 v10, v19, v13
	v_addc_co_u32_e32 v13, vcc, 0, v143, vcc
	v_pk_mul_f32 v[6:7], v[6:7], v[18:19] op_sel_hi:[1,0]
	v_pk_mul_f32 v[4:5], v[4:5], v[18:19] op_sel_hi:[1,0]
	v_max_f32_e32 v0, 0, v0
	v_max_f32_e32 v1, 0, v1
	v_max_f32_e32 v2, 0, v2
	v_cvt_pk_bf16_f32 v11, v14, v11
	global_store_dwordx4 v[12:13], v[8:11], off
	v_max_f32_e32 v3, 0, v3
	v_max_f32_e32 v4, 0, v4
	v_mul_f32_e32 v8, v0, v0
	v_max_f32_e32 v0, 0, v5
	v_mul_f32_e32 v5, v1, v1
	v_max_f32_e32 v1, 0, v6
	v_mul_f32_e32 v6, v2, v2
	v_max_f32_e32 v2, 0, v7
	v_mul_f32_e32 v0, v0, v0
	v_mul_f32_e32 v1, v1, v1
	v_mul_f32_e32 v2, v2, v2
	v_mul_f32_e32 v3, v3, v3
	s_andn2_b64 vcc, exec, s[38:39]
	s_mov_b64 s[10:11], -1
	v_mul_f32_e32 v4, v4, v4
	v_cvt_pk_bf16_f32 v0, v4, v0
	v_cvt_pk_bf16_f32 v1, v1, v2
	v_cvt_pk_bf16_f32 v2, v8, v5
	v_cvt_pk_bf16_f32 v3, v6, v3
	global_store_dwordx4 v[16:17], v[0:3], off offset:256
	s_cbranch_vccnz .LBB0_513
	s_andn2_b64 vcc, exec, s[0:1]
	s_cbranch_vccnz .LBB0_512
	s_barrier
